# v37: v32 + NA loop hand-pipelined with the structurally masked 16-key quarter of each wave skipped (bias/exp/cvt/PV of keys that lie outside every query's window in that wave are not issued; exact)
# baseline (speedup 1.0000x reference)
.LBB0_284:
	s_cmp_lg_u32 s16, 0
	s_cbranch_scc0 .Lna_it0
	v_readfirstlane_b32 s12, v234
	s_bitcmp1_b32 s12, 8
	s_cbranch_scc1 .Lna_loopb
	s_branch .Lna_loopa

.Lna_loopa:
	s_bitcmp1_b32 s36, 0
	s_cselect_b32 s12, 0x12000, 0
	s_add_i32 s17, s37, s12
	v_add3_u32 v248, s17, v146, v149
	v_add3_u32 v249, s17, v154, v146
	ds_read_b128 v[204:207], v248
	ds_read_b128 v[208:211], v248 offset:32
	ds_read_b128 v[212:215], v248 offset:64
	ds_read_b128 v[216:219], v248 offset:96
	ds_read_b128 v[220:223], v248 offset:4608
	ds_read_b128 v[224:227], v248 offset:4640
	ds_read_b128 v[228:231], v248 offset:4672
	ds_read_b128 v[244:247], v248 offset:4704
	s_cmpk_eq_i32 s16, 0x364
	s_cbranch_scc1 .Lna_noloada
	v_lshl_add_u64 v[2:3], v[152:153], 0, v[200:201]
	v_add_co_u32_e32 v4, vcc, 0x12d00000, v2
	v_lshl_add_u64 v[0:1], v[150:151], 0, v[200:201]
	s_nop 0
	v_addc_co_u32_e32 v5, vcc, 0, v3, vcc
	v_add_co_u32_e32 v6, vcc, 0x12e00000, v2
	global_load_dwordx4 v[120:123], v[0:1], off offset:-256
	global_load_dwordx4 v[124:127], v[0:1], off offset:-128
	v_addc_co_u32_e32 v7, vcc, 0, v3, vcc
	global_load_dwordx4 v[112:115], v[4:5], off offset:128
	global_load_dwordx4 v[116:119], v[6:7], off offset:128
	v_add_co_u32_e32 v4, vcc, 0x12f00000, v2
	global_load_dwordx4 v[128:131], v[0:1], off
	global_load_dwordx4 v[136:139], v[0:1], off offset:128
	v_addc_co_u32_e32 v5, vcc, 0, v3, vcc
	v_add_co_u32_e32 v0, vcc, 0x13000000, v2
	s_nop 1
	v_addc_co_u32_e32 v1, vcc, 0, v3, vcc
	global_load_dwordx4 v[132:135], v[4:5], off offset:128
	global_load_dwordx4 v[140:143], v[0:1], off offset:128
.Lna_noloada:
	v_mov_b32_e32 v203, 0xf149f2ca
	v_add_u32_e32 v189, s16, v155
	ds_read_b32 v189, v189
	v_add_u32_e32 v190, s16, v156
	ds_read_b32 v190, v190
	v_add_u32_e32 v191, s16, v157
	ds_read_b32 v191, v191
	v_add_u32_e32 v192, s16, v158
	ds_read_b32 v192, v192
	v_add_u32_e32 v193, s16, v159
	ds_read_b32 v193, v193
	v_add_u32_e32 v194, s16, v160
	ds_read_b32 v194, v194
	v_add_u32_e32 v195, s16, v161
	ds_read_b32 v195, v195
	s_waitcnt lgkmcnt(14)
	v_mfma_f32_32x32x16_bf16 v[0:15], v[204:207], v[96:99], v[64:79]
	s_waitcnt lgkmcnt(13)
	v_mfma_f32_32x32x16_bf16 v[0:15], v[208:211], v[100:103], v[0:15]
	s_waitcnt lgkmcnt(12)
	v_mfma_f32_32x32x16_bf16 v[0:15], v[212:215], v[104:107], v[0:15]
	s_waitcnt lgkmcnt(11)
	v_mfma_f32_32x32x16_bf16 v[0:15], v[216:219], v[108:111], v[0:15]
	ds_read_b128 v[80:83], v249 offset:9216
	ds_read_b128 v[84:87], v249 offset:13824
	ds_read_b128 v[88:91], v249 offset:9248
	ds_read_b128 v[92:95], v249 offset:13856
	s_waitcnt lgkmcnt(14)
	v_mfma_f32_32x32x16_bf16 v[16:31], v[220:223], v[96:99], v[64:79]
	s_waitcnt lgkmcnt(10)
	s_nop 4
	v_add_f32_e32 v0, v0, v189
	v_cndmask_b32_e64 v0, v203, v0, s[2:3]
	v_add_u32_e32 v189, s16, v162
	ds_read_b32 v189, v189
	s_waitcnt lgkmcnt(10)
	v_add_f32_e32 v1, v1, v190
	v_cndmask_b32_e64 v1, v203, v1, s[48:49]
	v_add_u32_e32 v190, s16, v163
	ds_read_b32 v190, v190
	v_mfma_f32_32x32x16_bf16 v[16:31], v[224:227], v[100:103], v[16:31]
	s_waitcnt lgkmcnt(10)
	v_add_f32_e32 v2, v2, v191
	v_cndmask_b32_e64 v2, v203, v2, s[52:53]
	v_add_u32_e32 v191, s16, v164
	ds_read_b32 v191, v191
	s_waitcnt lgkmcnt(10)
	v_add_f32_e32 v3, v3, v192
	v_cndmask_b32_e64 v3, v203, v3, s[54:55]
	v_add_u32_e32 v192, s16, v165
	ds_read_b32 v192, v192
	v_mfma_f32_32x32x16_bf16 v[16:31], v[228:231], v[104:107], v[16:31]
	s_waitcnt lgkmcnt(10)
	v_add_f32_e32 v4, v4, v193
	v_cndmask_b32_e64 v4, v203, v4, s[56:57]
	v_add_u32_e32 v193, s16, v166
	ds_read_b32 v193, v193
	s_waitcnt lgkmcnt(10)
	v_add_f32_e32 v5, v5, v194
	v_cndmask_b32_e64 v5, v203, v5, s[58:59]
	v_add_u32_e32 v194, s16, v167
	ds_read_b32 v194, v194
	v_mfma_f32_32x32x16_bf16 v[16:31], v[244:247], v[108:111], v[16:31]
	ds_read_b128 v[204:207], v249 offset:9280
	ds_read_b128 v[208:211], v249 offset:13888
	s_waitcnt lgkmcnt(12)
	v_add_f32_e32 v6, v6, v195
	v_cndmask_b32_e64 v6, v203, v6, s[60:61]
	v_add_u32_e32 v195, s16, v168
	ds_read_b32 v195, v195
	s_waitcnt lgkmcnt(8)
	v_add_f32_e32 v7, v7, v189
	v_cndmask_b32_e64 v7, v203, v7, s[62:63]
	v_add_u32_e32 v189, s16, v169
	ds_read_b32 v189, v189
	v_exp_f32_e32 v0, v0
	v_exp_f32_e32 v1, v1
	v_exp_f32_e32 v2, v2
	v_exp_f32_e32 v3, v3
	v_add_f32_e32 v232, v0, v2
	v_add_f32_e32 v233, v1, v3
	v_exp_f32_e32 v4, v4
	v_exp_f32_e32 v5, v5
	v_add_f32_e32 v232, v232, v4
	v_add_f32_e32 v233, v233, v5
	v_exp_f32_e32 v6, v6
	v_exp_f32_e32 v7, v7
	v_add_f32_e32 v232, v232, v6
	v_add_f32_e32 v233, v233, v7
	v_cvt_pk_bf16_f32 v0, v0, v1
	v_cvt_pk_bf16_f32 v1, v2, v3
	v_cvt_pk_bf16_f32 v2, v4, v5
	v_cvt_pk_bf16_f32 v3, v6, v7
	s_nop 1
	v_mfma_f32_32x32x16_bf16 v[48:63], v[80:83], v[0:3], v[48:63]
	v_mfma_f32_32x32x16_bf16 v[32:47], v[84:87], v[0:3], v[32:47]
	s_waitcnt lgkmcnt(8)
	v_add_f32_e32 v8, v8, v190
	v_cndmask_b32_e64 v8, v203, v8, s[64:65]
	v_add_u32_e32 v190, s16, v170
	ds_read_b32 v190, v190
	s_waitcnt lgkmcnt(8)
	v_add_f32_e32 v9, v9, v191
	v_cndmask_b32_e64 v9, v203, v9, s[66:67]
	v_add_u32_e32 v191, s16, v171
	ds_read_b32 v191, v191
	s_waitcnt lgkmcnt(8)
	v_add_f32_e32 v10, v10, v192
	v_cndmask_b32_e64 v10, v203, v10, s[68:69]
	v_add_u32_e32 v192, s16, v172
	ds_read_b32 v192, v192
	s_waitcnt lgkmcnt(8)
	v_add_f32_e32 v11, v11, v193
	v_cndmask_b32_e64 v11, v203, v11, s[70:71]
	v_add_u32_e32 v193, s16, v173
	ds_read_b32 v193, v193
	s_waitcnt lgkmcnt(8)
	v_add_f32_e32 v12, v12, v194
	v_cndmask_b32_e64 v12, v203, v12, s[72:73]
	v_add_u32_e32 v194, s16, v174
	ds_read_b32 v194, v194
	s_waitcnt lgkmcnt(6)
	v_add_f32_e32 v13, v13, v195
	v_cndmask_b32_e64 v13, v203, v13, s[74:75]
	v_add_u32_e32 v195, s16, v175
	ds_read_b32 v195, v195
	s_waitcnt lgkmcnt(6)
	v_add_f32_e32 v14, v14, v189
	v_cndmask_b32_e64 v14, v203, v14, s[76:77]
	v_add_u32_e32 v189, s16, v176
	ds_read_b32 v189, v189
	s_waitcnt lgkmcnt(6)
	v_add_f32_e32 v15, v15, v190
	v_cndmask_b32_e64 v15, v203, v15, s[78:79]
	v_add_u32_e32 v190, s16, v177
	ds_read_b32 v190, v190
	v_exp_f32_e32 v8, v8
	v_exp_f32_e32 v9, v9
	v_add_f32_e32 v232, v232, v8
	v_add_f32_e32 v233, v233, v9
	v_exp_f32_e32 v10, v10
	v_exp_f32_e32 v11, v11
	v_add_f32_e32 v232, v232, v10
	v_add_f32_e32 v233, v233, v11
	v_exp_f32_e32 v12, v12
	v_exp_f32_e32 v13, v13
	v_add_f32_e32 v232, v232, v12
	v_add_f32_e32 v233, v233, v13
	v_exp_f32_e32 v14, v14
	v_exp_f32_e32 v15, v15
	v_add_f32_e32 v232, v232, v14
	v_add_f32_e32 v233, v233, v15
	v_cvt_pk_bf16_f32 v8, v8, v9
	v_cvt_pk_bf16_f32 v9, v10, v11
	v_cvt_pk_bf16_f32 v10, v12, v13
	v_cvt_pk_bf16_f32 v11, v14, v15
	s_nop 1
	v_mfma_f32_32x32x16_bf16 v[48:63], v[88:91], v[8:11], v[48:63]
	v_mfma_f32_32x32x16_bf16 v[32:47], v[92:95], v[8:11], v[32:47]
	s_waitcnt lgkmcnt(6)
	v_add_f32_e32 v16, v16, v191
	v_cndmask_b32_e64 v16, v203, v16, s[80:81]
	v_add_u32_e32 v191, s16, v178
	ds_read_b32 v191, v191
	s_waitcnt lgkmcnt(6)
	v_add_f32_e32 v17, v17, v192
	v_cndmask_b32_e64 v17, v203, v17, s[82:83]
	s_waitcnt lgkmcnt(5)
	v_add_f32_e32 v18, v18, v193
	v_cndmask_b32_e64 v18, v203, v18, s[84:85]
	s_waitcnt lgkmcnt(4)
	v_add_f32_e32 v19, v19, v194
	v_cndmask_b32_e64 v19, v203, v19, s[86:87]
	s_waitcnt lgkmcnt(3)
	v_add_f32_e32 v20, v20, v195
	v_cndmask_b32_e64 v20, v203, v20, s[88:89]
	s_waitcnt lgkmcnt(2)
	v_add_f32_e32 v21, v21, v189
	v_cndmask_b32_e64 v21, v203, v21, s[90:91]
	s_waitcnt lgkmcnt(1)
	v_add_f32_e32 v22, v22, v190
	v_cndmask_b32_e64 v22, v203, v22, s[92:93]
	s_waitcnt lgkmcnt(0)
	v_add_f32_e32 v23, v23, v191
	v_cndmask_b32_e64 v23, v203, v23, s[94:95]
	v_exp_f32_e32 v16, v16
	v_exp_f32_e32 v17, v17
	v_add_f32_e32 v232, v232, v16
	v_add_f32_e32 v233, v233, v17
	v_exp_f32_e32 v18, v18
	v_exp_f32_e32 v19, v19
	v_add_f32_e32 v232, v232, v18
	v_add_f32_e32 v233, v233, v19
	v_exp_f32_e32 v20, v20
	v_exp_f32_e32 v21, v21
	v_add_f32_e32 v232, v232, v20
	v_add_f32_e32 v233, v233, v21
	v_exp_f32_e32 v22, v22
	v_exp_f32_e32 v23, v23
	v_add_f32_e32 v232, v232, v22
	v_add_f32_e32 v233, v233, v23
	v_cvt_pk_bf16_f32 v16, v16, v17
	v_cvt_pk_bf16_f32 v17, v18, v19
	v_cvt_pk_bf16_f32 v18, v20, v21
	v_cvt_pk_bf16_f32 v19, v22, v23
	s_nop 1
	v_mfma_f32_32x32x16_bf16 v[48:63], v[204:207], v[16:19], v[48:63]
	v_mfma_f32_32x32x16_bf16 v[32:47], v[208:211], v[16:19], v[32:47]
	v_add_f32_e32 v232, v232, v233
	s_add_i32 s36, s36, 1
	s_addk_i32 s16, 0x7c
	v_cmp_lt_f32_e32 vcc, s33, v232
	s_cbranch_vccz .Lna_norescalea
	s_nop 15
	v_and_b32_e32 v243, 64, v237
	v_xor_b32_e32 v242, 32, v237
	v_add_u32_e32 v243, 64, v243
	v_cmp_lt_i32_e32 vcc, v242, v243
	s_nop 1
	v_cndmask_b32_e32 v242, v237, v242, vcc
	v_lshlrev_b32_e32 v242, 2, v242
	ds_bpermute_b32 v242, v242, v232
	s_waitcnt lgkmcnt(0)
	v_add_f32_e32 v242, v242, v232
	v_frexp_exp_i32_f32_e32 v242, v242
	v_max_i32_e32 v242, 1, v242
	v_add_u32_e32 v242, -1, v242
	v_cvt_f32_u32_e32 v242, v242
	v_exp_f32_e64 v243, -v242
	v_add_f32_e32 v188, v188, v242
	v_xor_b32_e32 v64, 0x80000000, v188
	v_mul_f32_e32 v187, v187, v243
	v_mul_f32_e32 v232, v232, v243
	v_mul_f32_e32 v32, v32, v243
	v_mul_f32_e32 v33, v33, v243
	v_mul_f32_e32 v34, v34, v243
	v_mul_f32_e32 v35, v35, v243
	v_mul_f32_e32 v36, v36, v243
	v_mul_f32_e32 v37, v37, v243
	v_mul_f32_e32 v38, v38, v243
	v_mul_f32_e32 v39, v39, v243
	v_mul_f32_e32 v40, v40, v243
	v_mul_f32_e32 v41, v41, v243
	v_mul_f32_e32 v42, v42, v243
	v_mul_f32_e32 v43, v43, v243
	v_mul_f32_e32 v44, v44, v243
	v_mul_f32_e32 v45, v45, v243
	v_mul_f32_e32 v46, v46, v243
	v_mul_f32_e32 v47, v47, v243
	v_mul_f32_e32 v48, v48, v243
	v_mul_f32_e32 v49, v49, v243
	v_mul_f32_e32 v50, v50, v243
	v_mul_f32_e32 v51, v51, v243
	v_mul_f32_e32 v52, v52, v243
	v_mul_f32_e32 v53, v53, v243
	v_mul_f32_e32 v54, v54, v243
	v_mul_f32_e32 v55, v55, v243
	v_mul_f32_e32 v56, v56, v243
	v_mul_f32_e32 v57, v57, v243
	v_mul_f32_e32 v58, v58, v243
	v_mul_f32_e32 v59, v59, v243
	v_mul_f32_e32 v60, v60, v243
	v_mul_f32_e32 v61, v61, v243
	v_mul_f32_e32 v62, v62, v243
	v_mul_f32_e32 v63, v63, v243
	v_mov_b32_e32 v65, v64
	v_mov_b32_e32 v66, v64
	v_mov_b32_e32 v67, v64
	v_mov_b32_e32 v68, v64
	v_mov_b32_e32 v69, v64
	v_mov_b32_e32 v70, v64
	v_mov_b32_e32 v71, v64
	v_mov_b32_e32 v72, v64
	v_mov_b32_e32 v73, v64
	v_mov_b32_e32 v74, v64
	v_mov_b32_e32 v75, v64
	v_mov_b32_e32 v76, v64
	v_mov_b32_e32 v77, v64
	v_mov_b32_e32 v78, v64
	v_mov_b32_e32 v79, v64
.Lna_norescalea:
	v_add_f32_e32 v187, v187, v232
	v_lshl_add_u64 v[152:153], v[152:153], 0, s[26:27]
	v_lshl_add_u64 v[150:151], v[150:151], 0, s[28:29]
	s_cmpk_eq_i32 s16, 0x3e0
	s_cbranch_scc1 .Lna_lasta
	s_bitcmp1_b32 s36, 0
	s_cselect_b32 s12, 0x12000, 0
	v_add_u32_e32 v242, s12, v147
	s_waitcnt vmcnt(7)
	ds_write_b128 v242, v[120:123]
	s_waitcnt vmcnt(5)
	ds_write_b128 v242, v[112:115] offset:9216
	ds_write_b128 v242, v[124:127] offset:18432
	s_waitcnt vmcnt(4)
	ds_write_b128 v242, v[116:119] offset:27648
	s_waitcnt vmcnt(3)
	ds_write_b128 v242, v[128:131] offset:36864
	s_waitcnt vmcnt(1)
	ds_write_b128 v242, v[132:135] offset:46080
	ds_write_b128 v242, v[136:139] offset:55296
	s_waitcnt vmcnt(0)
	ds_write_b128 v242, v[140:143] offset:64512
	s_waitcnt lgkmcnt(0)
	s_barrier
	s_branch .Lna_loopa
.Lna_lasta:
	s_nop 7
	s_nop 7
	s_waitcnt lgkmcnt(0)
	s_barrier
	s_branch .LBB0_273

.Lna_noloadb:
	v_mov_b32_e32 v203, 0xf149f2ca
	v_add_u32_e32 v189, s16, v163
	ds_read_b32 v189, v189
	v_add_u32_e32 v190, s16, v164
	ds_read_b32 v190, v190
	v_add_u32_e32 v191, s16, v165
	ds_read_b32 v191, v191
	v_add_u32_e32 v192, s16, v166
	ds_read_b32 v192, v192
	v_add_u32_e32 v193, s16, v167
	ds_read_b32 v193, v193
	v_add_u32_e32 v194, s16, v168
	ds_read_b32 v194, v194
	v_add_u32_e32 v195, s16, v169
	ds_read_b32 v195, v195
	s_waitcnt lgkmcnt(14)
	v_mfma_f32_32x32x16_bf16 v[0:15], v[204:207], v[96:99], v[64:79]
	s_waitcnt lgkmcnt(13)
	v_mfma_f32_32x32x16_bf16 v[0:15], v[208:211], v[100:103], v[0:15]
	s_waitcnt lgkmcnt(12)
	v_mfma_f32_32x32x16_bf16 v[0:15], v[212:215], v[104:107], v[0:15]
	s_waitcnt lgkmcnt(11)
	v_mfma_f32_32x32x16_bf16 v[0:15], v[216:219], v[108:111], v[0:15]
	ds_read_b128 v[88:91], v249 offset:9248
	ds_read_b128 v[92:95], v249 offset:13856
	s_waitcnt lgkmcnt(12)
	v_mfma_f32_32x32x16_bf16 v[16:31], v[220:223], v[96:99], v[64:79]
	s_waitcnt lgkmcnt(11)
	v_mfma_f32_32x32x16_bf16 v[16:31], v[224:227], v[100:103], v[16:31]
	s_waitcnt lgkmcnt(10)
	v_mfma_f32_32x32x16_bf16 v[16:31], v[228:231], v[104:107], v[16:31]
	s_waitcnt lgkmcnt(9)
	v_mfma_f32_32x32x16_bf16 v[16:31], v[244:247], v[108:111], v[16:31]
	ds_read_b128 v[204:207], v249 offset:9280
	ds_read_b128 v[208:211], v249 offset:13888
	ds_read_b128 v[212:215], v249 offset:9312
	ds_read_b128 v[216:219], v249 offset:13920
	s_waitcnt lgkmcnt(12)
	v_add_f32_e32 v8, v8, v189
	v_cndmask_b32_e64 v8, v203, v8, s[64:65]
	v_add_u32_e32 v189, s16, v170
	ds_read_b32 v189, v189
	s_waitcnt lgkmcnt(12)
	v_add_f32_e32 v9, v9, v190
	v_cndmask_b32_e64 v9, v203, v9, s[66:67]
	v_add_u32_e32 v190, s16, v171
	ds_read_b32 v190, v190
	s_waitcnt lgkmcnt(12)
	v_add_f32_e32 v10, v10, v191
	v_cndmask_b32_e64 v10, v203, v10, s[68:69]
	v_add_u32_e32 v191, s16, v172
	ds_read_b32 v191, v191
	s_waitcnt lgkmcnt(12)
	v_add_f32_e32 v11, v11, v192
	v_cndmask_b32_e64 v11, v203, v11, s[70:71]
	v_add_u32_e32 v192, s16, v173
	ds_read_b32 v192, v192
	s_waitcnt lgkmcnt(12)
	v_add_f32_e32 v12, v12, v193
	v_cndmask_b32_e64 v12, v203, v12, s[72:73]
	v_add_u32_e32 v193, s16, v174
	ds_read_b32 v193, v193
	s_waitcnt lgkmcnt(12)
	v_add_f32_e32 v13, v13, v194
	v_cndmask_b32_e64 v13, v203, v13, s[74:75]
	v_add_u32_e32 v194, s16, v175
	ds_read_b32 v194, v194
	s_waitcnt lgkmcnt(12)
	v_add_f32_e32 v14, v14, v195
	v_cndmask_b32_e64 v14, v203, v14, s[76:77]
	v_add_u32_e32 v195, s16, v176
	ds_read_b32 v195, v195
	s_waitcnt lgkmcnt(6)
	v_add_f32_e32 v15, v15, v189
	v_cndmask_b32_e64 v15, v203, v15, s[78:79]
	v_add_u32_e32 v189, s16, v177
	ds_read_b32 v189, v189
	v_exp_f32_e32 v8, v8
	v_exp_f32_e32 v9, v9
	v_exp_f32_e32 v10, v10
	v_exp_f32_e32 v11, v11
	v_add_f32_e32 v232, v8, v10
	v_add_f32_e32 v233, v9, v11
	v_exp_f32_e32 v12, v12
	v_exp_f32_e32 v13, v13
	v_add_f32_e32 v232, v232, v12
	v_add_f32_e32 v233, v233, v13
	v_exp_f32_e32 v14, v14
	v_exp_f32_e32 v15, v15
	v_add_f32_e32 v232, v232, v14
	v_add_f32_e32 v233, v233, v15
	v_cvt_pk_bf16_f32 v8, v8, v9
	v_cvt_pk_bf16_f32 v9, v10, v11
	v_cvt_pk_bf16_f32 v10, v12, v13
	v_cvt_pk_bf16_f32 v11, v14, v15
	s_nop 1
	v_mfma_f32_32x32x16_bf16 v[48:63], v[88:91], v[8:11], v[48:63]
	v_mfma_f32_32x32x16_bf16 v[32:47], v[92:95], v[8:11], v[32:47]
	s_waitcnt lgkmcnt(6)
	v_add_f32_e32 v16, v16, v190
	v_cndmask_b32_e64 v16, v203, v16, s[80:81]
	v_add_u32_e32 v190, s16, v178
	ds_read_b32 v190, v190
	s_waitcnt lgkmcnt(6)
	v_add_f32_e32 v17, v17, v191
	v_cndmask_b32_e64 v17, v203, v17, s[82:83]
	v_add_u32_e32 v191, s16, v179
	ds_read_b32 v191, v191
	s_waitcnt lgkmcnt(6)
	v_add_f32_e32 v18, v18, v192
	v_cndmask_b32_e64 v18, v203, v18, s[84:85]
	v_add_u32_e32 v192, s16, v180
	ds_read_b32 v192, v192
	s_waitcnt lgkmcnt(6)
	v_add_f32_e32 v19, v19, v193
	v_cndmask_b32_e64 v19, v203, v19, s[86:87]
	v_add_u32_e32 v193, s16, v181
	ds_read_b32 v193, v193
	s_waitcnt lgkmcnt(6)
	v_add_f32_e32 v20, v20, v194
	v_cndmask_b32_e64 v20, v203, v20, s[88:89]
	v_add_u32_e32 v194, s16, v182
	ds_read_b32 v194, v194
	s_waitcnt lgkmcnt(6)
	v_add_f32_e32 v21, v21, v195
	v_cndmask_b32_e64 v21, v203, v21, s[90:91]
	v_add_u32_e32 v195, s16, v183
	ds_read_b32 v195, v195
	s_waitcnt lgkmcnt(6)
	v_add_f32_e32 v22, v22, v189
	v_cndmask_b32_e64 v22, v203, v22, s[92:93]
	v_add_u32_e32 v189, s16, v184
	ds_read_b32 v189, v189
	s_waitcnt lgkmcnt(6)
	v_add_f32_e32 v23, v23, v190
	v_cndmask_b32_e64 v23, v203, v23, s[94:95]
	v_add_u32_e32 v190, s16, v185
	ds_read_b32 v190, v190
	v_exp_f32_e32 v16, v16
	v_exp_f32_e32 v17, v17
	v_add_f32_e32 v232, v232, v16
	v_add_f32_e32 v233, v233, v17
	v_exp_f32_e32 v18, v18
	v_exp_f32_e32 v19, v19
	v_add_f32_e32 v232, v232, v18
	v_add_f32_e32 v233, v233, v19
	v_exp_f32_e32 v20, v20
	v_exp_f32_e32 v21, v21
	v_add_f32_e32 v232, v232, v20
	v_add_f32_e32 v233, v233, v21
	v_exp_f32_e32 v22, v22
	v_exp_f32_e32 v23, v23
	v_add_f32_e32 v232, v232, v22
	v_add_f32_e32 v233, v233, v23
	v_cvt_pk_bf16_f32 v16, v16, v17
	v_cvt_pk_bf16_f32 v17, v18, v19
	v_cvt_pk_bf16_f32 v18, v20, v21
	v_cvt_pk_bf16_f32 v19, v22, v23
	s_nop 1
	v_mfma_f32_32x32x16_bf16 v[48:63], v[204:207], v[16:19], v[48:63]
	v_mfma_f32_32x32x16_bf16 v[32:47], v[208:211], v[16:19], v[32:47]
	s_waitcnt lgkmcnt(6)
	v_add_f32_e32 v24, v24, v191
	v_cndmask_b32_e64 v24, v203, v24, s[96:97]
	v_add_u32_e32 v191, s16, v186
	ds_read_b32 v191, v191
	s_waitcnt lgkmcnt(6)
	v_add_f32_e32 v25, v25, v192
	v_cndmask_b32_e64 v25, v203, v25, s[40:41]
	s_waitcnt lgkmcnt(5)
	v_add_f32_e32 v26, v26, v193
	v_cndmask_b32_e64 v26, v203, v26, s[38:39]
	s_waitcnt lgkmcnt(4)
	v_add_f32_e32 v27, v27, v194
	v_cndmask_b32_e64 v27, v203, v27, s[44:45]
	s_waitcnt lgkmcnt(3)
	v_add_f32_e32 v28, v28, v195
	v_cndmask_b32_e64 v28, v203, v28, s[4:5]
	s_waitcnt lgkmcnt(2)
	v_add_f32_e32 v29, v29, v189
	v_cndmask_b32_e64 v29, v203, v29, s[42:43]
	s_waitcnt lgkmcnt(1)
	v_add_f32_e32 v30, v30, v190
	v_cndmask_b32_e64 v30, v203, v30, s[50:51]
	s_waitcnt lgkmcnt(0)
	v_add_f32_e32 v31, v31, v191
	v_cndmask_b32_e64 v31, v203, v31, s[6:7]
	v_exp_f32_e32 v24, v24
	v_exp_f32_e32 v25, v25
	v_add_f32_e32 v232, v232, v24
	v_add_f32_e32 v233, v233, v25
	v_exp_f32_e32 v26, v26
	v_exp_f32_e32 v27, v27
	v_add_f32_e32 v232, v232, v26
	v_add_f32_e32 v233, v233, v27
	v_exp_f32_e32 v28, v28
	v_exp_f32_e32 v29, v29
	v_add_f32_e32 v232, v232, v28
	v_add_f32_e32 v233, v233, v29
	v_exp_f32_e32 v30, v30
	v_exp_f32_e32 v31, v31
	v_add_f32_e32 v232, v232, v30
	v_add_f32_e32 v233, v233, v31
	v_cvt_pk_bf16_f32 v24, v24, v25
	v_cvt_pk_bf16_f32 v25, v26, v27
	v_cvt_pk_bf16_f32 v26, v28, v29
	v_cvt_pk_bf16_f32 v27, v30, v31
	s_nop 1
	v_mfma_f32_32x32x16_bf16 v[48:63], v[212:215], v[24:27], v[48:63]
	v_mfma_f32_32x32x16_bf16 v[32:47], v[216:219], v[24:27], v[32:47]
	v_add_f32_e32 v232, v232, v233
	s_add_i32 s36, s36, 1
	s_addk_i32 s16, 0x7c
	v_cmp_lt_f32_e32 vcc, s33, v232
	s_cbranch_vccz .Lna_norescaleb
	s_nop 15
	v_and_b32_e32 v243, 64, v237
	v_xor_b32_e32 v242, 32, v237
	v_add_u32_e32 v243, 64, v243
	v_cmp_lt_i32_e32 vcc, v242, v243
	s_nop 1
	v_cndmask_b32_e32 v242, v237, v242, vcc
	v_lshlrev_b32_e32 v242, 2, v242
	ds_bpermute_b32 v242, v242, v232
	s_waitcnt lgkmcnt(0)
	v_add_f32_e32 v242, v242, v232
	v_frexp_exp_i32_f32_e32 v242, v242
	v_max_i32_e32 v242, 1, v242
	v_add_u32_e32 v242, -1, v242
	v_cvt_f32_u32_e32 v242, v242
	v_exp_f32_e64 v243, -v242
	v_add_f32_e32 v188, v188, v242
	v_xor_b32_e32 v64, 0x80000000, v188
	v_mul_f32_e32 v187, v187, v243
	v_mul_f32_e32 v232, v232, v243
	v_mul_f32_e32 v32, v32, v243
	v_mul_f32_e32 v33, v33, v243
	v_mul_f32_e32 v34, v34, v243
	v_mul_f32_e32 v35, v35, v243
	v_mul_f32_e32 v36, v36, v243
	v_mul_f32_e32 v37, v37, v243
	v_mul_f32_e32 v38, v38, v243
	v_mul_f32_e32 v39, v39, v243
	v_mul_f32_e32 v40, v40, v243
	v_mul_f32_e32 v41, v41, v243
	v_mul_f32_e32 v42, v42, v243
	v_mul_f32_e32 v43, v43, v243
	v_mul_f32_e32 v44, v44, v243
	v_mul_f32_e32 v45, v45, v243
	v_mul_f32_e32 v46, v46, v243
	v_mul_f32_e32 v47, v47, v243
	v_mul_f32_e32 v48, v48, v243
	v_mul_f32_e32 v49, v49, v243
	v_mul_f32_e32 v50, v50, v243
	v_mul_f32_e32 v51, v51, v243
	v_mul_f32_e32 v52, v52, v243
	v_mul_f32_e32 v53, v53, v243
	v_mul_f32_e32 v54, v54, v243
	v_mul_f32_e32 v55, v55, v243
	v_mul_f32_e32 v56, v56, v243
	v_mul_f32_e32 v57, v57, v243
	v_mul_f32_e32 v58, v58, v243
	v_mul_f32_e32 v59, v59, v243
	v_mul_f32_e32 v60, v60, v243
	v_mul_f32_e32 v61, v61, v243
	v_mul_f32_e32 v62, v62, v243
	v_mul_f32_e32 v63, v63, v243
	v_mov_b32_e32 v65, v64
	v_mov_b32_e32 v66, v64
	v_mov_b32_e32 v67, v64
	v_mov_b32_e32 v68, v64
	v_mov_b32_e32 v69, v64
	v_mov_b32_e32 v70, v64
	v_mov_b32_e32 v71, v64
	v_mov_b32_e32 v72, v64
	v_mov_b32_e32 v73, v64
	v_mov_b32_e32 v74, v64
	v_mov_b32_e32 v75, v64
	v_mov_b32_e32 v76, v64
	v_mov_b32_e32 v77, v64
	v_mov_b32_e32 v78, v64
	v_mov_b32_e32 v79, v64
